# WKV loader wave: LRU and DMA loads use scalar-base + 32-bit offset addressing with immediate row offsets (about 40 fewer VALU per chunk)
# speedup vs baseline: 1.0024x; 1.0024x over previous
; #define WKV_BAR() do { asm volatile("s_waitcnt lgkmcnt(0)" ::: "memory"); __builtin_amdgcn_s_barrier(); asm volatile("" ::: "memory"); } while (0)
; #define WKV_FLUSH(cc) do { const LAS float* yb = ybuf + ((cc) & 1) * 512 + ls * 16 + part * 2; const unsigned row = rowbase + (unsigned)(cc) * 32u + ls - 1u;     \
;             if ((cc) > 0 || ls > 0) *(unsigned*)(ymix + row * 1024u + 512u + h * 64 + rg * 16 + part * 2) = cvt_pk_bf16(yb[0], yb[1]); } while (0)
; __device__ __forceinline__ void scan_wkv_prompt(PP P, int l, LAS unsigned char* lds, const Ids I) {
;     ...
;             for (int c = 0; c < 64; ++c) {
;                 WKV_BAR();
;                 asm volatile("s_waitcnt vmcnt(0)" ::: "memory");
;                 const unsigned lr = lrow0 + (unsigned)(c & 31) * 4u; bf16_t vla[4], vgx[4], vgb[4];
; #pragma unroll
;                 for (int k = 0; k < 4; ++k) { vla[k] = LAp[(lr + k) * 512u + lch]; vgx[k] = GXp[(lr + k) * 512u + lch]; vgb[k] = PRp[(lr + k) * (unsigned)INW + 512u + lch]; }
;                 if (c > 0) WKV_FLUSH(c - 1);
.LBB0_768:
	s_lshl_b32 s44, s66, 2
	s_and_b32 s44, s44, 0x7c
	v_or_b32_e32 v5, s44, v44
	v_lshl_or_b32 v144, v5, 9, v37
	s_waitcnt lgkmcnt(0)
	s_barrier
	v_lshlrev_b32_e32 v0, 1, v144
	s_waitcnt vmcnt(0)
	v_mul_lo_u32 v46, v5, s90
	global_load_ushort v57, v0, s[96:97]
	global_load_ushort v56, v0, s[10:11]
	v_or_b32_e32 v1, v46, v38
	v_lshlrev_b32_e32 v1, 1, v1
	global_load_ushort v55, v1, s[60:61]
	global_load_ushort v53, v0, s[96:97] offset:1024
	global_load_ushort v54, v0, s[10:11] offset:1024
	v_add_u32_e32 v2, 0x1600, v1
	global_load_ushort v52, v2, s[60:61]
	global_load_ushort v50, v0, s[96:97] offset:2048
	global_load_ushort v51, v0, s[10:11] offset:2048
	v_add_u32_e32 v3, 0x2c00, v1
	global_load_ushort v49, v3, s[60:61]
	global_load_ushort v47, v0, s[96:97] offset:3072
	s_cmp_lg_u32 s66, 0
	global_load_ushort v48, v0, s[10:11] offset:3072
	v_add_u32_e32 v2, 0x4200, v1
	global_load_ushort v46, v2, s[60:61]
	s_cselect_b64 s[44:45], -1, 0
	s_cmp_lg_u32 s66, 1
	s_cselect_b64 s[46:47], -1, 0
	s_or_b64 s[46:47], s[46:47], s[8:9]
	s_and_b64 s[46:47], s[44:45], s[46:47]
	s_and_saveexec_b64 s[44:45], s[46:47]
	s_cbranch_execz .LBB0_771
	s_add_i32 s46, s66, -1
	s_lshl_b32 s47, s46, 11
	s_and_b32 s47, s47, 0x800
	v_add_u32_e32 v0, s47, v28
	ds_read_b64 v[0:1], v0
	v_lshl_add_u32 v144, s46, 15, v39
	s_waitcnt lgkmcnt(0)
	v_cvt_pk_bf16_f32 v2, v0, v1
	v_lshl_add_u64 v[0:1], v[144:145], 1, v[14:15]
	global_store_dword v[0:1], v2, off offset:1024
	s_or_b64 exec, exec, s[44:45]
	s_cmp_gt_u32 s66, 61
	s_mov_b32 s90, 0xf800000
	s_cbranch_scc0 .LBB0_772

.LBB0_772:
	s_bitcmp1_b32 s66, 0
	s_cselect_b32 s44, 0x5400, 0
	v_lshl_add_u32 v0, s66, 14, v40
	s_add_i32 s44, s44, 0
	v_or_b32_e32 v144, v0, v36
	s_add_i32 s44, s44, 0x16000
	v_readlane_b32 s46, v254, 35
	s_add_i32 s45, s44, s0
	v_lshlrev_b32_e32 v2, 1, v144
	v_readlane_b32 s47, v254, 36
	s_mov_b32 m0, s45
	v_mov_b32_e32 v1, v145
	s_nop 3
	global_load_lds_dwordx4 v2, s[46:47]
	v_readlane_b32 s46, v254, 37
	s_add_i32 m0, s45, 0x1000
	v_readlane_b32 s47, v254, 38
	global_load_lds_dwordx4 v2, s[74:75]
	s_add_i32 m0, s45, 0x2000
	s_add_i32 s44, s44, s57
	s_nop 2
	global_load_lds_dwordx4 v2, s[46:47]
	s_add_i32 m0, s45, 0x3000
	s_nop 0
	global_load_lds_dwordx4 v2, s[52:53]
	s_add_i32 m0, s45, 0x4000
	v_lshl_add_u64 v[0:1], v[0:1], 1, v[6:7]
	global_load_lds_dwordx4 v2, s[70:71]
	s_add_i32 m0, s44, 0x5000
	s_nop 0
	global_load_lds_dword v[0:1], off
	s_add_i32 s67, s66, 1
	s_cmp_eq_u32 s66, 63
	s_cbranch_scc1 .LBB0_780

; __device__ __forceinline__ float bf2f(bf16_t h) { return __uint_as_float((unsigned)h << 16); }
; __device__ __forceinline__ bf16_t f2bf(float f) { return (bf16_t)(cvt_pk_bf16(f, 0.f) & 0xffffu); }
; __device__ __forceinline__ float gelu_tanh(float x) { const float u = 0.7978845608f * (x + 0.044715f * x * x * x); return 0.5f * x * (1.0f + tanh_f(u)); }
; #define WKV_BAR() do { asm volatile("s_waitcnt lgkmcnt(0)" ::: "memory"); __builtin_amdgcn_s_barrier(); asm volatile("" ::: "memory"); } while (0)
; #define WKV_FLUSH(cc) do { const LAS float* yb = ybuf + ((cc) & 1) * 512 + ls * 16 + part * 2; const unsigned row = rowbase + (unsigned)(cc) * 32u + ls - 1u;     \
;             if ((cc) > 0 || ls > 0) *(unsigned*)(ymix + row * 1024u + 512u + h * 64 + rg * 16 + part * 2) = cvt_pk_bf16(yb[0], yb[1]); } while (0)
; __device__ __forceinline__ void scan_wkv_prompt(PP P, int l, LAS unsigned char* lds, const Ids I) {
;     ...
; #pragma unroll 1
;             for (int c = 0; c < 64; ++c) {
;                 WKV_BAR();
;                 asm volatile("s_waitcnt vmcnt(0)" ::: "memory");
;                 const unsigned lr = lrow0 + (unsigned)(c & 31) * 4u; bf16_t vla[4], vgx[4], vgb[4];
; #pragma unroll
;                 for (int k = 0; k < 4; ++k) { vla[k] = LAp[(lr + k) * 512u + lch]; vgx[k] = GXp[(lr + k) * 512u + lch]; vgb[k] = PRp[(lr + k) * (unsigned)INW + 512u + lch]; }
;                 if (c > 0) WKV_FLUSH(c - 1);
;                 if (c + 2 < 64) WKV_DMA(c + 2);
;                 if (c + 1 < 64) WKV_CONVERT(c + 1);
;                 if (c == 32) { for (int q = 0; q < lck; ++q) { const f32x2 ab = LAB[q * 16 + lcl]; lh = ab.x * lh + ab.y; } }
; #pragma unroll
;                 for (int k = 0; k < 4; ++k) { const float la = bf2f(vla[k]), gx = bf2f(vgx[k]); const float a = __expf(la), bb = sqrtf(fmaxf(1.f - a * a, 0.f)) * gx;
;                     if (c < 32) { lB = a * lB + bb; lA *= a; }
;                     else { lh = a * lh + bb; ymix[(lr + k) * 1024u + lch] = f2bf(lh * gelu_tanh(bf2f(vgb[k]))); } }
;                 if (c == 31) LAB[lck * 16 + lcl] = (f32x2){lA, lB};
;             }
.LBB0_801:
	s_cmp_eq_u32 s67, 64
	s_cbranch_scc1 .LBB0_803
	s_mov_b32 s66, s67
	s_branch .LBB0_768
	s_nop 0
	s_nop 0
	s_nop 0
	s_nop 0
	s_nop 0
	s_nop 0
	s_nop 0
	s_nop 0
	s_nop 0
	s_nop 0
	s_nop 0
	s_nop 0
	s_nop 0
	s_nop 0
	s_nop 0
	s_nop 0
	s_nop 0
	s_nop 0
	s_nop 0
	s_nop 0
	s_nop 0
	s_nop 0
	s_nop 0
	s_nop 0
	s_nop 0
	s_nop 0
	s_nop 0
	s_nop 0
	s_nop 0
	s_nop 0
	s_nop 0
	s_nop 0
	s_nop 0
	s_nop 0
	s_nop 0
	s_nop 0
	s_nop 0
	s_nop 0
	s_nop 0
	s_nop 0
	s_nop 0
	s_nop 0
	s_nop 0
	s_nop 0
	s_nop 0
	s_nop 0
	s_nop 0
	s_nop 0
	s_nop 0
